# P4 EpiRes: x (residual) loads issued 3 row-groups ahead into free fragment registers, counted vmcnt instead of 32 serialized store-load round trips
# speedup vs baseline: 1.0239x; 1.0105x over previous
; __device__ __forceinline__ float sum_x16(float v) { return v + __shfl_xor(v, 16); }
; __device__ __forceinline__ float sum_x32(float v) { return v + __shfl_xor(v, 32); }
; __device__ __forceinline__ unsigned cvt_pk_bf16(float lo, float hi) { unsigned r; asm volatile("v_cvt_pk_bf16_f32 %0, %1, %2" : "=v"(r) : "v"(lo), "v"(hi)); return r; }
;     __device__ __forceinline__ void operator()(const f32x4 (&acc)[2][2][4][2], const Unit& u, int wr, int wc, int fr, int fq) const {
;     ...
;                 const int row = u.pm * BM + ai * HALF + wr * 64 + m * 16 + fr;
;                 float s = 0.f;
; #pragma unroll
;                 for (int bj = 0; bj < 2; ++bj)
; #pragma unroll
;                     for (int n = 0; n < 2; ++n) {
;                         const int col = u.pn * BM + bj * HALF + wc * 32 + n * 16 + fq * 4;
;                         f32x4 h = acc[ai][bj][m][n];
;                         if (mode) { const u32x2 hb = *(const u32x2*)(HB + (size_t)row * DM + col); h[0] += bflo(hb.x); h[1] += bfhi(hb.x); h[2] += bflo(hb.y); h[3] += bfhi(hb.y); }
;                         else h = h + *(const f32x4*)(xp + (size_t)row * DM + col);
;                         u32x2 w; w.x = cvt_pk_bf16(h[0], h[1]); w.y = cvt_pk_bf16(h[2], h[3]);
;                         *(u32x2*)(HB + (size_t)row * DM + col) = w;
;                         s += (h[0] * h[0] + h[1] * h[1]) + (h[2] * h[2] + h[3] * h[3]);
;                     }
;                 s = sum_x32(sum_x16(s));
;                 if (fq == 0) ss[(size_t)row * 16 + u.pn * 4 + wc] = s;
.LBB0_1018:
	v_lshl_add_u32 v142, s96, 8, v146
	v_ashrrev_i32_e32 v143, 31, v142
	v_lshl_or_b32 v140, s21, 8, v148
	v_lshlrev_b64 v[150:151], 12, v[142:143]
	v_ashrrev_i32_e32 v141, 31, v140
	v_lshl_add_u64 v[150:151], s[44:45], 0, v[150:151]
	v_lshl_add_u64 v[154:155], v[140:141], 2, v[150:151]
	v_lshlrev_b32_e32 v208, 12, v142
	v_lshl_add_u32 v208, v140, 2, v208
	global_load_dwordx4 v[160:163], v208, s[44:45]
	global_load_dwordx4 v[164:167], v208, s[44:45] offset:64
	global_load_dwordx4 v[168:171], v208, s[44:45] offset:512
	global_load_dwordx4 v[172:175], v208, s[44:45] offset:576
	v_add_u32_e32 v209, 0x10000, v208
	global_load_dwordx4 v[176:179], v209, s[44:45]
	global_load_dwordx4 v[180:183], v209, s[44:45] offset:64
	global_load_dwordx4 v[184:187], v209, s[44:45] offset:512
	global_load_dwordx4 v[188:191], v209, s[44:45] offset:576
	v_add_u32_e32 v209, 0x20000, v208
	global_load_dwordx4 v[192:195], v209, s[44:45]
	global_load_dwordx4 v[196:199], v209, s[44:45] offset:64
	global_load_dwordx4 v[200:203], v209, s[44:45] offset:512
	global_load_dwordx4 v[204:207], v209, s[44:45] offset:576
	v_lshlrev_b64 v[156:157], 11, v[142:143]
	v_lshl_add_u64 v[156:157], s[2:3], 0, v[156:157]
	v_lshl_add_u64 v[156:157], v[140:141], 1, v[156:157]
	s_lshl_b32 s14, s21, 2
	s_ashr_i32 s15, s14, 31
	s_waitcnt vmcnt(11)
	v_pk_add_f32 v[162:163], v[126:127], v[162:163]
	v_pk_add_f32 v[160:161], v[124:125], v[160:161]
	s_nop 0
	v_cvt_pk_bf16_f32 v124, v160, v161
	v_cvt_pk_bf16_f32 v125, v162, v163
	global_store_dwordx2 v[156:157], v[124:125], off
	v_mul_f32_e32 v161, v161, v161
	v_mul_f32_e32 v163, v163, v163
	v_fmac_f32_e32 v161, v160, v160
	v_fmac_f32_e32 v163, v162, v162
	v_add_f32_e32 v160, v161, v163
	s_waitcnt vmcnt(11)
	v_pk_add_f32 v[166:167], v[122:123], v[166:167]
	v_pk_add_f32 v[164:165], v[120:121], v[164:165]
	s_nop 0
	v_cvt_pk_bf16_f32 v120, v164, v165
	v_cvt_pk_bf16_f32 v121, v166, v167
	global_store_dwordx2 v[156:157], v[120:121], off offset:32
	v_mul_f32_e32 v165, v165, v165
	v_mul_f32_e32 v167, v167, v167
	v_fmac_f32_e32 v165, v164, v164
	v_fmac_f32_e32 v167, v166, v166
	v_add_f32_e32 v164, v165, v167
	v_add_f32_e32 v164, v160, v164
	s_waitcnt vmcnt(11)
	v_pk_add_f32 v[170:171], v[118:119], v[170:171]
	v_pk_add_f32 v[158:159], v[116:117], v[168:169]
	s_nop 0
	v_cvt_pk_bf16_f32 v116, v158, v159
	v_cvt_pk_bf16_f32 v117, v170, v171
	global_store_dwordx2 v[156:157], v[116:117], off offset:256
	v_and_b32_e32 v117, 64, v145
	v_mul_f32_e32 v165, v159, v159
	v_mul_f32_e32 v171, v171, v171
	v_xor_b32_e32 v116, 16, v145
	v_add_u32_e32 v117, 64, v117
	v_fmac_f32_e32 v165, v158, v158
	v_fmac_f32_e32 v171, v170, v170
	v_cmp_lt_i32_e32 vcc, v116, v117
	v_add_f32_e32 v170, v165, v171
	v_add_f32_e32 v170, v164, v170
	v_cndmask_b32_e32 v116, v145, v116, vcc
	v_lshlrev_b32_e32 v116, 2, v116
	s_waitcnt vmcnt(11)
	v_pk_add_f32 v[174:175], v[114:115], v[174:175]
	v_pk_add_f32 v[172:173], v[112:113], v[172:173]
	v_mul_f32_e32 v113, v175, v175
	v_mul_f32_e32 v112, v173, v173
	v_fmac_f32_e32 v112, v172, v172
	v_fmac_f32_e32 v113, v174, v174
	v_add_f32_e32 v112, v112, v113
	v_add_f32_e32 v112, v170, v112
	ds_bpermute_b32 v113, v116, v112
	v_xor_b32_e32 v114, 32, v145
	v_cmp_lt_i32_e32 vcc, v114, v117
	v_cvt_pk_bf16_f32 v172, v172, v173
	v_cvt_pk_bf16_f32 v173, v174, v175
	s_waitcnt lgkmcnt(0)
	v_add_f32_e32 v112, v112, v113
	global_store_dwordx2 v[156:157], v[172:173], off offset:288
	v_cndmask_b32_e32 v114, v145, v114, vcc
	v_lshlrev_b32_e32 v114, 2, v114
	ds_bpermute_b32 v113, v114, v112
	s_and_saveexec_b64 s[16:17], s[38:39]
	s_cbranch_execz .LBB0_1020

; __device__ __forceinline__ float sum_x16(float v) { return v + __shfl_xor(v, 16); }
; __device__ __forceinline__ float sum_x32(float v) { return v + __shfl_xor(v, 32); }
; __device__ __forceinline__ unsigned cvt_pk_bf16(float lo, float hi) { unsigned r; asm volatile("v_cvt_pk_bf16_f32 %0, %1, %2" : "=v"(r) : "v"(lo), "v"(hi)); return r; }
;     __device__ __forceinline__ void operator()(const f32x4 (&acc)[2][2][4][2], const Unit& u, int wr, int wc, int fr, int fq) const {
;     ...
;                 const int row = u.pm * BM + ai * HALF + wr * 64 + m * 16 + fr;
;                 float s = 0.f;
; #pragma unroll
;                 for (int bj = 0; bj < 2; ++bj)
; #pragma unroll
;                     for (int n = 0; n < 2; ++n) {
;                         const int col = u.pn * BM + bj * HALF + wc * 32 + n * 16 + fq * 4;
;                         f32x4 h = acc[ai][bj][m][n];
;                         if (mode) { const u32x2 hb = *(const u32x2*)(HB + (size_t)row * DM + col); h[0] += bflo(hb.x); h[1] += bfhi(hb.x); h[2] += bflo(hb.y); h[3] += bfhi(hb.y); }
;                         else h = h + *(const f32x4*)(xp + (size_t)row * DM + col);
;                         u32x2 w; w.x = cvt_pk_bf16(h[0], h[1]); w.y = cvt_pk_bf16(h[2], h[3]);
;                         *(u32x2*)(HB + (size_t)row * DM + col) = w;
;                         s += (h[0] * h[0] + h[1] * h[1]) + (h[2] * h[2] + h[3] * h[3]);
;                     }
;                 s = sum_x32(sum_x16(s));
;                 if (fq == 0) ss[(size_t)row * 16 + u.pn * 4 + wc] = s;
	v_lshlrev_b64 v[172:173], 6, v[142:143]
	v_lshl_add_u64 v[172:173], s[34:35], 0, v[172:173]
	v_lshl_add_u64 v[172:173], s[14:15], 2, v[172:173]
	s_lshl_b32 s96, s29, 2
	v_lshl_add_u64 v[172:173], v[172:173], 0, s[96:97]
	s_waitcnt lgkmcnt(0)
	v_add_f32_e32 v112, v112, v113
	global_store_dword v[172:173], v112, off
.LBB0_1020:
	s_or_b64 exec, exec, s[16:17]
	v_add_u32_e32 v209, 0x30000, v208
	global_load_dwordx4 v[160:163], v209, s[44:45]
	global_load_dwordx4 v[164:167], v209, s[44:45] offset:64
	global_load_dwordx4 v[168:171], v209, s[44:45] offset:512
	global_load_dwordx4 v[172:175], v209, s[44:45] offset:576
	v_or_b32_e32 v112, 16, v142
	s_waitcnt lgkmcnt(0)
	v_ashrrev_i32_e32 v113, 31, v112
	v_lshlrev_b64 v[118:119], 12, v[112:113]
	v_lshl_add_u64 v[118:119], s[44:45], 0, v[118:119]
	v_lshl_add_u64 v[122:123], v[140:141], 2, v[118:119]
	v_lshlrev_b64 v[124:125], 11, v[112:113]
	v_lshl_add_u64 v[124:125], s[2:3], 0, v[124:125]
	v_lshl_add_u64 v[124:125], v[140:141], 1, v[124:125]
	s_waitcnt vmcnt(15)
	v_pk_add_f32 v[178:179], v[110:111], v[178:179]
	v_pk_add_f32 v[176:177], v[108:109], v[176:177]
	v_mul_f32_e32 v117, v179, v179
	v_cvt_pk_bf16_f32 v108, v176, v177
	v_cvt_pk_bf16_f32 v109, v178, v179
	global_store_dwordx2 v[124:125], v[108:109], off
	v_mul_f32_e32 v115, v177, v177
	v_fmac_f32_e32 v115, v176, v176
	v_fmac_f32_e32 v117, v178, v178
	v_add_f32_e32 v115, v115, v117
	s_waitcnt vmcnt(15)
	v_pk_add_f32 v[182:183], v[106:107], v[182:183]
	v_pk_add_f32 v[180:181], v[104:105], v[180:181]
	s_nop 0
	v_cvt_pk_bf16_f32 v104, v180, v181
	v_cvt_pk_bf16_f32 v105, v182, v183
	global_store_dwordx2 v[124:125], v[104:105], off offset:32
	v_mul_f32_e32 v181, v181, v181
	v_mul_f32_e32 v183, v183, v183
	v_fmac_f32_e32 v181, v180, v180
	v_fmac_f32_e32 v183, v182, v182
	v_add_f32_e32 v180, v181, v183
	v_add_f32_e32 v180, v115, v180
	s_waitcnt vmcnt(15)
	v_pk_add_f32 v[186:187], v[102:103], v[186:187]
	v_pk_add_f32 v[184:185], v[100:101], v[184:185]
	s_nop 0
	v_cvt_pk_bf16_f32 v100, v184, v185
	v_cvt_pk_bf16_f32 v101, v186, v187
	global_store_dwordx2 v[124:125], v[100:101], off offset:256
	v_mul_f32_e32 v185, v185, v185
	v_mul_f32_e32 v187, v187, v187
	v_fmac_f32_e32 v185, v184, v184
	v_fmac_f32_e32 v187, v186, v186
	v_add_f32_e32 v184, v185, v187
	v_add_f32_e32 v184, v180, v184
	s_waitcnt vmcnt(15)
	v_pk_add_f32 v[98:99], v[98:99], v[190:191]
	v_pk_add_f32 v[188:189], v[96:97], v[188:189]
	v_mul_f32_e32 v97, v99, v99
	v_mul_f32_e32 v96, v189, v189
	v_fmac_f32_e32 v96, v188, v188
	v_fmac_f32_e32 v97, v98, v98
	v_add_f32_e32 v96, v96, v97
	v_add_f32_e32 v96, v184, v96
	ds_bpermute_b32 v97, v116, v96
	v_cvt_pk_bf16_f32 v188, v188, v189
	v_cvt_pk_bf16_f32 v189, v98, v99
	global_store_dwordx2 v[124:125], v[188:189], off offset:288
	s_waitcnt lgkmcnt(0)
	v_add_f32_e32 v96, v96, v97
	ds_bpermute_b32 v97, v114, v96
	s_and_saveexec_b64 s[16:17], s[38:39]
	s_cbranch_execz .LBB0_1022

; __device__ __forceinline__ float sum_x16(float v) { return v + __shfl_xor(v, 16); }
; __device__ __forceinline__ float sum_x32(float v) { return v + __shfl_xor(v, 32); }
; __device__ __forceinline__ unsigned cvt_pk_bf16(float lo, float hi) { unsigned r; asm volatile("v_cvt_pk_bf16_f32 %0, %1, %2" : "=v"(r) : "v"(lo), "v"(hi)); return r; }
;     __device__ __forceinline__ void operator()(const f32x4 (&acc)[2][2][4][2], const Unit& u, int wr, int wc, int fr, int fq) const {
;     ...
;                 const int row = u.pm * BM + ai * HALF + wr * 64 + m * 16 + fr;
;                 float s = 0.f;
; #pragma unroll
;                 for (int bj = 0; bj < 2; ++bj)
; #pragma unroll
;                     for (int n = 0; n < 2; ++n) {
;                         const int col = u.pn * BM + bj * HALF + wc * 32 + n * 16 + fq * 4;
;                         f32x4 h = acc[ai][bj][m][n];
;                         if (mode) { const u32x2 hb = *(const u32x2*)(HB + (size_t)row * DM + col); h[0] += bflo(hb.x); h[1] += bfhi(hb.x); h[2] += bflo(hb.y); h[3] += bfhi(hb.y); }
;                         else h = h + *(const f32x4*)(xp + (size_t)row * DM + col);
;                         u32x2 w; w.x = cvt_pk_bf16(h[0], h[1]); w.y = cvt_pk_bf16(h[2], h[3]);
;                         *(u32x2*)(HB + (size_t)row * DM + col) = w;
;                         s += (h[0] * h[0] + h[1] * h[1]) + (h[2] * h[2] + h[3] * h[3]);
;                     }
;                 s = sum_x32(sum_x16(s));
;                 if (fq == 0) ss[(size_t)row * 16 + u.pn * 4 + wc] = s;
	v_lshlrev_b64 v[98:99], 6, v[112:113]
	v_lshl_add_u64 v[98:99], s[34:35], 0, v[98:99]
	v_lshl_add_u64 v[98:99], s[14:15], 2, v[98:99]
	s_lshl_b32 s96, s29, 2
	v_lshl_add_u64 v[98:99], v[98:99], 0, s[96:97]
	s_waitcnt lgkmcnt(0)
	v_add_f32_e32 v96, v96, v97
	global_store_dword v[98:99], v96, off
.LBB0_1022:
	s_or_b64 exec, exec, s[16:17]
	v_add_u32_e32 v209, 0x80000, v208
	global_load_dwordx4 v[176:179], v209, s[44:45]
	global_load_dwordx4 v[180:183], v209, s[44:45] offset:64
	global_load_dwordx4 v[184:187], v209, s[44:45] offset:512
	global_load_dwordx4 v[188:191], v209, s[44:45] offset:576
	v_or_b32_e32 v96, 32, v142
	s_waitcnt lgkmcnt(0)
	v_ashrrev_i32_e32 v97, 31, v96
	v_lshlrev_b64 v[98:99], 12, v[96:97]
	v_lshl_add_u64 v[98:99], s[44:45], 0, v[98:99]
	v_lshl_add_u64 v[102:103], v[140:141], 2, v[98:99]
	v_lshlrev_b64 v[104:105], 11, v[96:97]
	v_lshl_add_u64 v[104:105], s[2:3], 0, v[104:105]
	v_lshl_add_u64 v[104:105], v[140:141], 1, v[104:105]
	s_waitcnt vmcnt(19)
	v_pk_add_f32 v[194:195], v[94:95], v[194:195]
	v_pk_add_f32 v[192:193], v[92:93], v[192:193]
	s_nop 0
	v_cvt_pk_bf16_f32 v92, v192, v193
	v_cvt_pk_bf16_f32 v93, v194, v195
	global_store_dwordx2 v[104:105], v[92:93], off
	v_mul_f32_e32 v193, v193, v193
	v_mul_f32_e32 v195, v195, v195
	v_fmac_f32_e32 v193, v192, v192
	v_fmac_f32_e32 v195, v194, v194
	v_add_f32_e32 v192, v193, v195
	s_waitcnt vmcnt(19)
	v_pk_add_f32 v[198:199], v[90:91], v[198:199]
	v_pk_add_f32 v[196:197], v[88:89], v[196:197]
	s_nop 0
	v_cvt_pk_bf16_f32 v88, v196, v197
	v_cvt_pk_bf16_f32 v89, v198, v199
	global_store_dwordx2 v[104:105], v[88:89], off offset:32
	v_mul_f32_e32 v197, v197, v197
	v_mul_f32_e32 v199, v199, v199
	v_fmac_f32_e32 v197, v196, v196
	v_fmac_f32_e32 v199, v198, v198
	v_add_f32_e32 v196, v197, v199
	v_add_f32_e32 v196, v192, v196
	s_waitcnt vmcnt(19)
	v_pk_add_f32 v[202:203], v[86:87], v[202:203]
	v_pk_add_f32 v[200:201], v[84:85], v[200:201]
	s_nop 0
	v_cvt_pk_bf16_f32 v84, v200, v201
	v_cvt_pk_bf16_f32 v85, v202, v203
	global_store_dwordx2 v[104:105], v[84:85], off offset:256
	v_mul_f32_e32 v201, v201, v201
	v_mul_f32_e32 v203, v203, v203
	v_fmac_f32_e32 v201, v200, v200
	v_fmac_f32_e32 v203, v202, v202
	v_add_f32_e32 v200, v201, v203
	v_add_f32_e32 v200, v196, v200
	s_waitcnt vmcnt(19)
	v_pk_add_f32 v[82:83], v[82:83], v[206:207]
	v_pk_add_f32 v[204:205], v[80:81], v[204:205]
	v_mul_f32_e32 v81, v83, v83
	v_mul_f32_e32 v80, v205, v205
	v_fmac_f32_e32 v80, v204, v204
	v_fmac_f32_e32 v81, v82, v82
	v_add_f32_e32 v80, v80, v81
	v_add_f32_e32 v80, v200, v80
	ds_bpermute_b32 v81, v116, v80
	v_cvt_pk_bf16_f32 v204, v204, v205
	v_cvt_pk_bf16_f32 v205, v82, v83
	global_store_dwordx2 v[104:105], v[204:205], off offset:288
	s_waitcnt lgkmcnt(0)
	v_add_f32_e32 v80, v80, v81
	ds_bpermute_b32 v81, v114, v80
	s_and_saveexec_b64 s[16:17], s[38:39]
	s_cbranch_execz .LBB0_1024

; __device__ __forceinline__ float sum_x16(float v) { return v + __shfl_xor(v, 16); }
; __device__ __forceinline__ float sum_x32(float v) { return v + __shfl_xor(v, 32); }
; __device__ __forceinline__ unsigned cvt_pk_bf16(float lo, float hi) { unsigned r; asm volatile("v_cvt_pk_bf16_f32 %0, %1, %2" : "=v"(r) : "v"(lo), "v"(hi)); return r; }
;     __device__ __forceinline__ void operator()(const f32x4 (&acc)[2][2][4][2], const Unit& u, int wr, int wc, int fr, int fq) const {
;     ...
;                 const int row = u.pm * BM + ai * HALF + wr * 64 + m * 16 + fr;
;                 float s = 0.f;
; #pragma unroll
;                 for (int bj = 0; bj < 2; ++bj)
; #pragma unroll
;                     for (int n = 0; n < 2; ++n) {
;                         const int col = u.pn * BM + bj * HALF + wc * 32 + n * 16 + fq * 4;
;                         f32x4 h = acc[ai][bj][m][n];
;                         if (mode) { const u32x2 hb = *(const u32x2*)(HB + (size_t)row * DM + col); h[0] += bflo(hb.x); h[1] += bfhi(hb.x); h[2] += bflo(hb.y); h[3] += bfhi(hb.y); }
;                         else h = h + *(const f32x4*)(xp + (size_t)row * DM + col);
;                         u32x2 w; w.x = cvt_pk_bf16(h[0], h[1]); w.y = cvt_pk_bf16(h[2], h[3]);
;                         *(u32x2*)(HB + (size_t)row * DM + col) = w;
;                         s += (h[0] * h[0] + h[1] * h[1]) + (h[2] * h[2] + h[3] * h[3]);
;                     }
;                 s = sum_x32(sum_x16(s));
;                 if (fq == 0) ss[(size_t)row * 16 + u.pn * 4 + wc] = s;
	v_lshlrev_b64 v[82:83], 6, v[96:97]
	v_lshl_add_u64 v[82:83], s[34:35], 0, v[82:83]
	v_lshl_add_u64 v[82:83], s[14:15], 2, v[82:83]
	s_lshl_b32 s96, s29, 2
	v_lshl_add_u64 v[82:83], v[82:83], 0, s[96:97]
	s_waitcnt lgkmcnt(0)
	v_add_f32_e32 v80, v80, v81
	global_store_dword v[82:83], v80, off
.LBB0_1024:
	s_or_b64 exec, exec, s[16:17]
	v_add_u32_e32 v209, 0x90000, v208
	global_load_dwordx4 v[192:195], v209, s[44:45]
	global_load_dwordx4 v[196:199], v209, s[44:45] offset:64
	global_load_dwordx4 v[200:203], v209, s[44:45] offset:512
	global_load_dwordx4 v[204:207], v209, s[44:45] offset:576
	v_or_b32_e32 v80, 48, v142
	s_waitcnt lgkmcnt(0)
	v_ashrrev_i32_e32 v81, 31, v80
	v_lshlrev_b64 v[82:83], 12, v[80:81]
	v_lshl_add_u64 v[82:83], s[44:45], 0, v[82:83]
	v_lshl_add_u64 v[86:87], v[140:141], 2, v[82:83]
	v_lshlrev_b64 v[88:89], 11, v[80:81]
	v_lshl_add_u64 v[88:89], s[2:3], 0, v[88:89]
	v_lshl_add_u64 v[88:89], v[140:141], 1, v[88:89]
	s_waitcnt vmcnt(19)
	v_pk_add_f32 v[162:163], v[78:79], v[162:163]
	v_pk_add_f32 v[160:161], v[76:77], v[160:161]
	s_nop 0
	v_cvt_pk_bf16_f32 v76, v160, v161
	v_cvt_pk_bf16_f32 v77, v162, v163
	global_store_dwordx2 v[88:89], v[76:77], off
	v_mul_f32_e32 v161, v161, v161
	v_mul_f32_e32 v163, v163, v163
	v_fmac_f32_e32 v161, v160, v160
	v_fmac_f32_e32 v163, v162, v162
	v_add_f32_e32 v160, v161, v163
	s_waitcnt vmcnt(19)
	v_pk_add_f32 v[166:167], v[74:75], v[166:167]
	v_pk_add_f32 v[164:165], v[72:73], v[164:165]
	s_nop 0
	v_cvt_pk_bf16_f32 v72, v164, v165
	v_cvt_pk_bf16_f32 v73, v166, v167
	global_store_dwordx2 v[88:89], v[72:73], off offset:32
	v_mul_f32_e32 v165, v165, v165
	v_mul_f32_e32 v167, v167, v167
	v_fmac_f32_e32 v165, v164, v164
	v_fmac_f32_e32 v167, v166, v166
	v_add_f32_e32 v164, v165, v167
	v_add_f32_e32 v164, v160, v164
	s_waitcnt vmcnt(19)
	v_pk_add_f32 v[170:171], v[70:71], v[170:171]
	v_pk_add_f32 v[168:169], v[68:69], v[168:169]
	s_nop 0
	v_cvt_pk_bf16_f32 v68, v168, v169
	v_cvt_pk_bf16_f32 v69, v170, v171
	global_store_dwordx2 v[88:89], v[68:69], off offset:256
	v_mul_f32_e32 v169, v169, v169
	v_mul_f32_e32 v171, v171, v171
	v_fmac_f32_e32 v169, v168, v168
	v_fmac_f32_e32 v171, v170, v170
	v_add_f32_e32 v168, v169, v171
	v_add_f32_e32 v168, v164, v168
	s_waitcnt vmcnt(19)
	v_pk_add_f32 v[66:67], v[66:67], v[174:175]
	v_pk_add_f32 v[172:173], v[64:65], v[172:173]
	v_mul_f32_e32 v65, v67, v67
	v_mul_f32_e32 v64, v173, v173
	v_fmac_f32_e32 v64, v172, v172
	v_fmac_f32_e32 v65, v66, v66
	v_add_f32_e32 v64, v64, v65
	v_add_f32_e32 v64, v168, v64
	ds_bpermute_b32 v65, v116, v64
	v_cvt_pk_bf16_f32 v172, v172, v173
	v_cvt_pk_bf16_f32 v173, v66, v67
	global_store_dwordx2 v[88:89], v[172:173], off offset:288
	s_waitcnt lgkmcnt(0)
	v_add_f32_e32 v64, v64, v65
	ds_bpermute_b32 v65, v114, v64
	s_and_saveexec_b64 s[16:17], s[38:39]
	s_cbranch_execz .LBB0_1026

; __device__ __forceinline__ float sum_x16(float v) { return v + __shfl_xor(v, 16); }
; __device__ __forceinline__ float sum_x32(float v) { return v + __shfl_xor(v, 32); }
; __device__ __forceinline__ unsigned cvt_pk_bf16(float lo, float hi) { unsigned r; asm volatile("v_cvt_pk_bf16_f32 %0, %1, %2" : "=v"(r) : "v"(lo), "v"(hi)); return r; }
;     __device__ __forceinline__ void operator()(const f32x4 (&acc)[2][2][4][2], const Unit& u, int wr, int wc, int fr, int fq) const {
;     ...
;                 const int row = u.pm * BM + ai * HALF + wr * 64 + m * 16 + fr;
;                 float s = 0.f;
; #pragma unroll
;                 for (int bj = 0; bj < 2; ++bj)
; #pragma unroll
;                     for (int n = 0; n < 2; ++n) {
;                         const int col = u.pn * BM + bj * HALF + wc * 32 + n * 16 + fq * 4;
;                         f32x4 h = acc[ai][bj][m][n];
;                         if (mode) { const u32x2 hb = *(const u32x2*)(HB + (size_t)row * DM + col); h[0] += bflo(hb.x); h[1] += bfhi(hb.x); h[2] += bflo(hb.y); h[3] += bfhi(hb.y); }
;                         else h = h + *(const f32x4*)(xp + (size_t)row * DM + col);
;                         u32x2 w; w.x = cvt_pk_bf16(h[0], h[1]); w.y = cvt_pk_bf16(h[2], h[3]);
;                         *(u32x2*)(HB + (size_t)row * DM + col) = w;
;                         s += (h[0] * h[0] + h[1] * h[1]) + (h[2] * h[2] + h[3] * h[3]);
;                     }
;                 s = sum_x32(sum_x16(s));
;                 if (fq == 0) ss[(size_t)row * 16 + u.pn * 4 + wc] = s;
	v_lshlrev_b64 v[66:67], 6, v[80:81]
	v_lshl_add_u64 v[66:67], s[34:35], 0, v[66:67]
	v_lshl_add_u64 v[66:67], s[14:15], 2, v[66:67]
	s_lshl_b32 s96, s29, 2
	v_lshl_add_u64 v[66:67], v[66:67], 0, s[96:97]
	s_waitcnt lgkmcnt(0)
	v_add_f32_e32 v64, v64, v65
	global_store_dword v[66:67], v64, off
.LBB0_1026:
	s_or_b64 exec, exec, s[16:17]
	v_add_u32_e32 v209, 0xa0000, v208
	global_load_dwordx4 v[160:163], v209, s[44:45]
	global_load_dwordx4 v[164:167], v209, s[44:45] offset:64
	global_load_dwordx4 v[168:171], v209, s[44:45] offset:512
	global_load_dwordx4 v[172:175], v209, s[44:45] offset:576
	v_add_u32_e32 v64, 0x80, v142
	s_waitcnt lgkmcnt(0)
	v_ashrrev_i32_e32 v65, 31, v64
	v_lshlrev_b64 v[66:67], 12, v[64:65]
	v_lshl_add_u64 v[66:67], s[44:45], 0, v[66:67]
	v_lshl_add_u64 v[70:71], v[140:141], 2, v[66:67]
	v_lshlrev_b64 v[72:73], 11, v[64:65]
	v_lshl_add_u64 v[72:73], s[2:3], 0, v[72:73]
	v_lshl_add_u64 v[72:73], v[140:141], 1, v[72:73]
	s_waitcnt vmcnt(19)
	v_pk_add_f32 v[178:179], v[62:63], v[178:179]
	v_pk_add_f32 v[176:177], v[60:61], v[176:177]
	s_nop 0
	v_cvt_pk_bf16_f32 v60, v176, v177
	v_cvt_pk_bf16_f32 v61, v178, v179
	global_store_dwordx2 v[72:73], v[60:61], off
	v_mul_f32_e32 v177, v177, v177
	v_mul_f32_e32 v179, v179, v179
	v_fmac_f32_e32 v177, v176, v176
	v_fmac_f32_e32 v179, v178, v178
	v_add_f32_e32 v176, v177, v179
	s_waitcnt vmcnt(19)
	v_pk_add_f32 v[182:183], v[58:59], v[182:183]
	v_pk_add_f32 v[180:181], v[56:57], v[180:181]
	s_nop 0
	v_cvt_pk_bf16_f32 v56, v180, v181
	v_cvt_pk_bf16_f32 v57, v182, v183
	global_store_dwordx2 v[72:73], v[56:57], off offset:32
	v_mul_f32_e32 v181, v181, v181
	v_mul_f32_e32 v183, v183, v183
	v_fmac_f32_e32 v181, v180, v180
	v_fmac_f32_e32 v183, v182, v182
	v_add_f32_e32 v180, v181, v183
	v_add_f32_e32 v180, v176, v180
	s_waitcnt vmcnt(19)
	v_pk_add_f32 v[186:187], v[54:55], v[186:187]
	v_pk_add_f32 v[184:185], v[52:53], v[184:185]
	s_nop 0
	v_cvt_pk_bf16_f32 v52, v184, v185
	v_cvt_pk_bf16_f32 v53, v186, v187
	global_store_dwordx2 v[72:73], v[52:53], off offset:256
	v_mul_f32_e32 v185, v185, v185
	v_mul_f32_e32 v187, v187, v187
	v_fmac_f32_e32 v185, v184, v184
	v_fmac_f32_e32 v187, v186, v186
	v_add_f32_e32 v184, v185, v187
	v_add_f32_e32 v184, v180, v184
	s_waitcnt vmcnt(19)
	v_pk_add_f32 v[50:51], v[50:51], v[190:191]
	v_pk_add_f32 v[188:189], v[48:49], v[188:189]
	v_mul_f32_e32 v49, v51, v51
	v_mul_f32_e32 v48, v189, v189
	v_fmac_f32_e32 v48, v188, v188
	v_fmac_f32_e32 v49, v50, v50
	v_add_f32_e32 v48, v48, v49
	v_add_f32_e32 v48, v184, v48
	ds_bpermute_b32 v49, v116, v48
	v_cvt_pk_bf16_f32 v188, v188, v189
	v_cvt_pk_bf16_f32 v189, v50, v51
	global_store_dwordx2 v[72:73], v[188:189], off offset:288
	s_waitcnt lgkmcnt(0)
	v_add_f32_e32 v48, v48, v49
	ds_bpermute_b32 v49, v114, v48
	s_and_saveexec_b64 s[16:17], s[38:39]
	s_cbranch_execz .LBB0_1028

; __device__ __forceinline__ float sum_x16(float v) { return v + __shfl_xor(v, 16); }
; __device__ __forceinline__ float sum_x32(float v) { return v + __shfl_xor(v, 32); }
; __device__ __forceinline__ unsigned cvt_pk_bf16(float lo, float hi) { unsigned r; asm volatile("v_cvt_pk_bf16_f32 %0, %1, %2" : "=v"(r) : "v"(lo), "v"(hi)); return r; }
;     __device__ __forceinline__ void operator()(const f32x4 (&acc)[2][2][4][2], const Unit& u, int wr, int wc, int fr, int fq) const {
;     ...
;                 const int row = u.pm * BM + ai * HALF + wr * 64 + m * 16 + fr;
;                 float s = 0.f;
; #pragma unroll
;                 for (int bj = 0; bj < 2; ++bj)
; #pragma unroll
;                     for (int n = 0; n < 2; ++n) {
;                         const int col = u.pn * BM + bj * HALF + wc * 32 + n * 16 + fq * 4;
;                         f32x4 h = acc[ai][bj][m][n];
;                         if (mode) { const u32x2 hb = *(const u32x2*)(HB + (size_t)row * DM + col); h[0] += bflo(hb.x); h[1] += bfhi(hb.x); h[2] += bflo(hb.y); h[3] += bfhi(hb.y); }
;                         else h = h + *(const f32x4*)(xp + (size_t)row * DM + col);
;                         u32x2 w; w.x = cvt_pk_bf16(h[0], h[1]); w.y = cvt_pk_bf16(h[2], h[3]);
;                         *(u32x2*)(HB + (size_t)row * DM + col) = w;
;                         s += (h[0] * h[0] + h[1] * h[1]) + (h[2] * h[2] + h[3] * h[3]);
;                     }
;                 s = sum_x32(sum_x16(s));
;                 if (fq == 0) ss[(size_t)row * 16 + u.pn * 4 + wc] = s;
	v_lshlrev_b64 v[50:51], 6, v[64:65]
	v_lshl_add_u64 v[50:51], s[34:35], 0, v[50:51]
	v_lshl_add_u64 v[50:51], s[14:15], 2, v[50:51]
	s_lshl_b32 s96, s29, 2
	v_lshl_add_u64 v[50:51], v[50:51], 0, s[96:97]
	s_waitcnt lgkmcnt(0)
	v_add_f32_e32 v48, v48, v49
	global_store_dword v[50:51], v48, off
.LBB0_1028:
	s_or_b64 exec, exec, s[16:17]
	v_add_u32_e32 v209, 0xb0000, v208
	global_load_dwordx4 v[176:179], v209, s[44:45]
	global_load_dwordx4 v[180:183], v209, s[44:45] offset:64
	global_load_dwordx4 v[184:187], v209, s[44:45] offset:512
	global_load_dwordx4 v[188:191], v209, s[44:45] offset:576
	v_add_u32_e32 v48, 0x90, v142
	s_waitcnt lgkmcnt(0)
	v_ashrrev_i32_e32 v49, 31, v48
	v_lshlrev_b64 v[50:51], 12, v[48:49]
	v_lshl_add_u64 v[50:51], s[44:45], 0, v[50:51]
	v_lshl_add_u64 v[54:55], v[140:141], 2, v[50:51]
	v_lshlrev_b64 v[56:57], 11, v[48:49]
	v_lshl_add_u64 v[56:57], s[2:3], 0, v[56:57]
	v_lshl_add_u64 v[56:57], v[140:141], 1, v[56:57]
	s_waitcnt vmcnt(19)
	v_pk_add_f32 v[194:195], v[46:47], v[194:195]
	v_pk_add_f32 v[192:193], v[44:45], v[192:193]
	s_nop 0
	v_cvt_pk_bf16_f32 v44, v192, v193
	v_cvt_pk_bf16_f32 v45, v194, v195
	global_store_dwordx2 v[56:57], v[44:45], off
	v_mul_f32_e32 v193, v193, v193
	v_mul_f32_e32 v195, v195, v195
	v_fmac_f32_e32 v193, v192, v192
	v_fmac_f32_e32 v195, v194, v194
	v_add_f32_e32 v192, v193, v195
	s_waitcnt vmcnt(19)
	v_pk_add_f32 v[198:199], v[42:43], v[198:199]
	v_pk_add_f32 v[196:197], v[40:41], v[196:197]
	s_nop 0
	v_cvt_pk_bf16_f32 v40, v196, v197
	v_cvt_pk_bf16_f32 v41, v198, v199
	global_store_dwordx2 v[56:57], v[40:41], off offset:32
	v_mul_f32_e32 v197, v197, v197
	v_mul_f32_e32 v199, v199, v199
	v_fmac_f32_e32 v197, v196, v196
	v_fmac_f32_e32 v199, v198, v198
	v_add_f32_e32 v196, v197, v199
	v_add_f32_e32 v196, v192, v196
	s_waitcnt vmcnt(19)
	v_pk_add_f32 v[202:203], v[38:39], v[202:203]
	v_pk_add_f32 v[200:201], v[36:37], v[200:201]
	s_nop 0
	v_cvt_pk_bf16_f32 v36, v200, v201
	v_cvt_pk_bf16_f32 v37, v202, v203
	global_store_dwordx2 v[56:57], v[36:37], off offset:256
	v_mul_f32_e32 v201, v201, v201
	v_mul_f32_e32 v203, v203, v203
	v_fmac_f32_e32 v201, v200, v200
	v_fmac_f32_e32 v203, v202, v202
	v_add_f32_e32 v200, v201, v203
	v_add_f32_e32 v200, v196, v200
	s_waitcnt vmcnt(19)
	v_pk_add_f32 v[34:35], v[34:35], v[206:207]
	v_pk_add_f32 v[204:205], v[32:33], v[204:205]
	v_mul_f32_e32 v33, v35, v35
	v_mul_f32_e32 v32, v205, v205
	v_fmac_f32_e32 v32, v204, v204
	v_fmac_f32_e32 v33, v34, v34
	v_add_f32_e32 v32, v32, v33
	v_add_f32_e32 v32, v200, v32
	ds_bpermute_b32 v33, v116, v32
	v_cvt_pk_bf16_f32 v204, v204, v205
	v_cvt_pk_bf16_f32 v205, v34, v35
	global_store_dwordx2 v[56:57], v[204:205], off offset:288
	s_waitcnt lgkmcnt(0)
	v_add_f32_e32 v32, v32, v33
	ds_bpermute_b32 v33, v114, v32
	s_and_saveexec_b64 s[16:17], s[38:39]
	s_cbranch_execz .LBB0_1030

; __device__ __forceinline__ float sum_x16(float v) { return v + __shfl_xor(v, 16); }
; __device__ __forceinline__ float sum_x32(float v) { return v + __shfl_xor(v, 32); }
; __device__ __forceinline__ unsigned cvt_pk_bf16(float lo, float hi) { unsigned r; asm volatile("v_cvt_pk_bf16_f32 %0, %1, %2" : "=v"(r) : "v"(lo), "v"(hi)); return r; }
;     __device__ __forceinline__ void operator()(const f32x4 (&acc)[2][2][4][2], const Unit& u, int wr, int wc, int fr, int fq) const {
;     ...
;                 const int row = u.pm * BM + ai * HALF + wr * 64 + m * 16 + fr;
;                 float s = 0.f;
; #pragma unroll
;                 for (int bj = 0; bj < 2; ++bj)
; #pragma unroll
;                     for (int n = 0; n < 2; ++n) {
;                         const int col = u.pn * BM + bj * HALF + wc * 32 + n * 16 + fq * 4;
;                         f32x4 h = acc[ai][bj][m][n];
;                         if (mode) { const u32x2 hb = *(const u32x2*)(HB + (size_t)row * DM + col); h[0] += bflo(hb.x); h[1] += bfhi(hb.x); h[2] += bflo(hb.y); h[3] += bfhi(hb.y); }
;                         else h = h + *(const f32x4*)(xp + (size_t)row * DM + col);
;                         u32x2 w; w.x = cvt_pk_bf16(h[0], h[1]); w.y = cvt_pk_bf16(h[2], h[3]);
;                         *(u32x2*)(HB + (size_t)row * DM + col) = w;
;                         s += (h[0] * h[0] + h[1] * h[1]) + (h[2] * h[2] + h[3] * h[3]);
;                     }
;                 s = sum_x32(sum_x16(s));
;                 if (fq == 0) ss[(size_t)row * 16 + u.pn * 4 + wc] = s;
	v_lshlrev_b64 v[34:35], 6, v[48:49]
	v_lshl_add_u64 v[34:35], s[34:35], 0, v[34:35]
	v_lshl_add_u64 v[34:35], s[14:15], 2, v[34:35]
	s_lshl_b32 s96, s29, 2
	v_lshl_add_u64 v[34:35], v[34:35], 0, s[96:97]
	s_waitcnt lgkmcnt(0)
	v_add_f32_e32 v32, v32, v33
	global_store_dword v[34:35], v32, off
.LBB0_1030:
	s_or_b64 exec, exec, s[16:17]
	v_add_u32_e32 v32, 0xa0, v142
	s_waitcnt lgkmcnt(0)
	v_ashrrev_i32_e32 v33, 31, v32
	v_lshlrev_b64 v[34:35], 12, v[32:33]
	v_lshl_add_u64 v[34:35], s[44:45], 0, v[34:35]
	v_lshl_add_u64 v[38:39], v[140:141], 2, v[34:35]
	v_lshlrev_b64 v[40:41], 11, v[32:33]
	v_lshl_add_u64 v[40:41], s[2:3], 0, v[40:41]
	v_lshl_add_u64 v[40:41], v[140:141], 1, v[40:41]
	s_waitcnt vmcnt(15)
	v_pk_add_f32 v[162:163], v[30:31], v[162:163]
	v_pk_add_f32 v[160:161], v[28:29], v[160:161]
	s_nop 0
	v_cvt_pk_bf16_f32 v28, v160, v161
	v_cvt_pk_bf16_f32 v29, v162, v163
	global_store_dwordx2 v[40:41], v[28:29], off
	v_mul_f32_e32 v161, v161, v161
	v_mul_f32_e32 v163, v163, v163
	v_fmac_f32_e32 v161, v160, v160
	v_fmac_f32_e32 v163, v162, v162
	v_add_f32_e32 v160, v161, v163
	s_waitcnt vmcnt(15)
	v_pk_add_f32 v[166:167], v[26:27], v[166:167]
	v_pk_add_f32 v[164:165], v[24:25], v[164:165]
	s_nop 0
	v_cvt_pk_bf16_f32 v24, v164, v165
	v_cvt_pk_bf16_f32 v25, v166, v167
	global_store_dwordx2 v[40:41], v[24:25], off offset:32
	v_mul_f32_e32 v165, v165, v165
	v_mul_f32_e32 v167, v167, v167
	v_fmac_f32_e32 v165, v164, v164
	v_fmac_f32_e32 v167, v166, v166
	v_add_f32_e32 v164, v165, v167
	v_add_f32_e32 v164, v160, v164
	s_waitcnt vmcnt(15)
	v_pk_add_f32 v[170:171], v[22:23], v[170:171]
	v_pk_add_f32 v[168:169], v[20:21], v[168:169]
	s_nop 0
	v_cvt_pk_bf16_f32 v20, v168, v169
	v_cvt_pk_bf16_f32 v21, v170, v171
	global_store_dwordx2 v[40:41], v[20:21], off offset:256
	v_mul_f32_e32 v169, v169, v169
	v_mul_f32_e32 v171, v171, v171
	v_fmac_f32_e32 v169, v168, v168
	v_fmac_f32_e32 v171, v170, v170
	v_add_f32_e32 v168, v169, v171
	v_add_f32_e32 v168, v164, v168
	s_waitcnt vmcnt(15)
	v_pk_add_f32 v[18:19], v[18:19], v[174:175]
	v_pk_add_f32 v[172:173], v[16:17], v[172:173]
	v_mul_f32_e32 v17, v19, v19
	v_mul_f32_e32 v16, v173, v173
	v_fmac_f32_e32 v16, v172, v172
	v_fmac_f32_e32 v17, v18, v18
	v_add_f32_e32 v16, v16, v17
	v_add_f32_e32 v16, v168, v16
	ds_bpermute_b32 v17, v116, v16
	v_cvt_pk_bf16_f32 v172, v172, v173
	v_cvt_pk_bf16_f32 v173, v18, v19
	global_store_dwordx2 v[40:41], v[172:173], off offset:288
	s_waitcnt lgkmcnt(0)
	v_add_f32_e32 v16, v16, v17
	ds_bpermute_b32 v17, v114, v16
	s_and_saveexec_b64 s[16:17], s[38:39]
	s_cbranch_execz .LBB0_1032

; __device__ __forceinline__ float sum_x16(float v) { return v + __shfl_xor(v, 16); }
; __device__ __forceinline__ float sum_x32(float v) { return v + __shfl_xor(v, 32); }
; __device__ __forceinline__ unsigned cvt_pk_bf16(float lo, float hi) { unsigned r; asm volatile("v_cvt_pk_bf16_f32 %0, %1, %2" : "=v"(r) : "v"(lo), "v"(hi)); return r; }
;     __device__ __forceinline__ void operator()(const f32x4 (&acc)[2][2][4][2], const Unit& u, int wr, int wc, int fr, int fq) const {
;     ...
;                 const int row = u.pm * BM + ai * HALF + wr * 64 + m * 16 + fr;
;                 float s = 0.f;
; #pragma unroll
;                 for (int bj = 0; bj < 2; ++bj)
; #pragma unroll
;                     for (int n = 0; n < 2; ++n) {
;                         const int col = u.pn * BM + bj * HALF + wc * 32 + n * 16 + fq * 4;
;                         f32x4 h = acc[ai][bj][m][n];
;                         if (mode) { const u32x2 hb = *(const u32x2*)(HB + (size_t)row * DM + col); h[0] += bflo(hb.x); h[1] += bfhi(hb.x); h[2] += bflo(hb.y); h[3] += bfhi(hb.y); }
;                         else h = h + *(const f32x4*)(xp + (size_t)row * DM + col);
;                         u32x2 w; w.x = cvt_pk_bf16(h[0], h[1]); w.y = cvt_pk_bf16(h[2], h[3]);
;                         *(u32x2*)(HB + (size_t)row * DM + col) = w;
;                         s += (h[0] * h[0] + h[1] * h[1]) + (h[2] * h[2] + h[3] * h[3]);
;                     }
;                 s = sum_x32(sum_x16(s));
;                 if (fq == 0) ss[(size_t)row * 16 + u.pn * 4 + wc] = s;
	v_lshlrev_b64 v[18:19], 6, v[32:33]
	v_lshl_add_u64 v[18:19], s[34:35], 0, v[18:19]
	v_lshl_add_u64 v[18:19], s[14:15], 2, v[18:19]
	s_lshl_b32 s96, s29, 2
	v_lshl_add_u64 v[18:19], v[18:19], 0, s[96:97]
	s_waitcnt lgkmcnt(0)
	v_add_f32_e32 v16, v16, v17
	global_store_dword v[18:19], v16, off
.LBB0_1032:
	s_or_b64 exec, exec, s[16:17]
	v_add_u32_e32 v16, 0xb0, v142
	s_waitcnt lgkmcnt(0)
	v_ashrrev_i32_e32 v17, 31, v16
	v_lshlrev_b64 v[18:19], 12, v[16:17]
	v_lshl_add_u64 v[18:19], s[44:45], 0, v[18:19]
	v_lshl_add_u64 v[22:23], v[140:141], 2, v[18:19]
	v_lshlrev_b64 v[24:25], 11, v[16:17]
	v_lshl_add_u64 v[24:25], s[2:3], 0, v[24:25]
	v_lshl_add_u64 v[24:25], v[140:141], 1, v[24:25]
	s_waitcnt vmcnt(11)
	v_pk_add_f32 v[178:179], v[14:15], v[178:179]
	v_pk_add_f32 v[176:177], v[12:13], v[176:177]
	s_nop 0
	v_cvt_pk_bf16_f32 v12, v176, v177
	v_cvt_pk_bf16_f32 v13, v178, v179
	global_store_dwordx2 v[24:25], v[12:13], off
	v_mul_f32_e32 v177, v177, v177
	v_mul_f32_e32 v179, v179, v179
	v_fmac_f32_e32 v177, v176, v176
	v_fmac_f32_e32 v179, v178, v178
	v_add_f32_e32 v176, v177, v179
	s_waitcnt vmcnt(11)
	v_pk_add_f32 v[182:183], v[10:11], v[182:183]
	v_pk_add_f32 v[180:181], v[8:9], v[180:181]
	s_nop 0
	v_cvt_pk_bf16_f32 v8, v180, v181
	v_cvt_pk_bf16_f32 v9, v182, v183
	global_store_dwordx2 v[24:25], v[8:9], off offset:32
	v_mul_f32_e32 v181, v181, v181
	v_mul_f32_e32 v183, v183, v183
	v_fmac_f32_e32 v181, v180, v180
	v_fmac_f32_e32 v183, v182, v182
	v_add_f32_e32 v180, v181, v183
	v_add_f32_e32 v180, v176, v180
	s_waitcnt vmcnt(11)
	v_pk_add_f32 v[186:187], v[6:7], v[186:187]
	v_pk_add_f32 v[184:185], v[4:5], v[184:185]
	s_nop 0
	v_cvt_pk_bf16_f32 v4, v184, v185
	v_cvt_pk_bf16_f32 v5, v186, v187
	global_store_dwordx2 v[24:25], v[4:5], off offset:256
	v_mul_f32_e32 v185, v185, v185
	v_mul_f32_e32 v187, v187, v187
	v_fmac_f32_e32 v185, v184, v184
	v_fmac_f32_e32 v187, v186, v186
	v_add_f32_e32 v184, v185, v187
	v_add_f32_e32 v184, v180, v184
	s_waitcnt vmcnt(11)
	v_pk_add_f32 v[2:3], v[2:3], v[190:191]
	v_pk_add_f32 v[188:189], v[0:1], v[188:189]
	v_mul_f32_e32 v1, v3, v3
	v_mul_f32_e32 v0, v189, v189
	v_fmac_f32_e32 v0, v188, v188
	v_fmac_f32_e32 v1, v2, v2
	v_add_f32_e32 v0, v0, v1
	v_add_f32_e32 v0, v184, v0
	ds_bpermute_b32 v1, v116, v0
	v_cvt_pk_bf16_f32 v188, v188, v189
	v_cvt_pk_bf16_f32 v189, v2, v3
	global_store_dwordx2 v[24:25], v[188:189], off offset:288
	s_waitcnt lgkmcnt(0)
	v_add_f32_e32 v0, v0, v1
	ds_bpermute_b32 v1, v114, v0
	s_and_saveexec_b64 s[16:17], s[38:39]
	s_cbranch_execz .LBB0_1034

;     __device__ __forceinline__ void operator()(const f32x4 (&acc)[2][2][4][2], const Unit& u, int wr, int wc, int fr, int fq) const {
;     ...
;                 if (fq == 0) ss[(size_t)row * 16 + u.pn * 4 + wc] = s;
	v_lshlrev_b64 v[2:3], 6, v[16:17]
	v_lshl_add_u64 v[2:3], s[34:35], 0, v[2:3]
	v_lshl_add_u64 v[2:3], s[14:15], 2, v[2:3]
	s_lshl_b32 s96, s29, 2
	v_lshl_add_u64 v[2:3], v[2:3], 0, s[96:97]
	s_waitcnt lgkmcnt(0)
	v_add_f32_e32 v0, v0, v1
	global_store_dword v[2:3], v0, off
